# P10 residual loop: first-half parameter loads (8 dwordx4) hoisted into the top load block, 4 store-ack waits removed
# speedup vs baseline: 1.0036x; 1.0020x over previous
.LBB0_912:
	s_ashr_i32 s98, s2, 11
	s_mul_i32 s98, s98, 9
	s_ashr_i32 s99, s98, 31
	s_lshl_b64 s[98:99], s[98:99], 12
	s_add_u32 s98, s14, s98
	s_addc_u32 s99, s15, s99
	s_add_u32 s98, s98, 0x5000
	s_addc_u32 s99, s99, 0
	s_and_b32 s0, s18, 0x8000
	s_and_b32 s1, s7, 0xfffff000
	s_add_i32 s0, s0, s1
	s_and_b32 s1, s4, 0xffc
	s_or_b32 s0, s0, s1
	s_ashr_i32 s1, s0, 31
	s_lshl_b64 s[0:1], s[0:1], 11
	s_ashr_i32 s5, s4, 31
	v_lshl_add_u64 v[64:65], v[4:5], 0, s[0:1]
	s_lshl_b64 s[10:11], s[4:5], 11
	v_lshl_add_u64 v[0:1], v[6:7], 0, s[10:11]
	global_load_dwordx2 v[80:81], v[64:65], off
	global_load_dwordx2 v[2:3], v[0:1], off
	s_add_i32 s0, s4, 1
	s_ashr_i32 s1, s0, 31
	s_lshl_b64 s[0:1], s[0:1], 11
	v_lshl_add_u64 v[40:41], v[6:7], 0, s[0:1]
	s_add_i32 s0, s4, 2
	s_ashr_i32 s1, s0, 31
	s_lshl_b64 s[0:1], s[0:1], 11
	v_lshl_add_u64 v[88:89], v[6:7], 0, s[0:1]
	s_movk_i32 s0, 0x1000
	v_add_co_u32_e32 v90, vcc, s0, v64
	s_add_i32 s0, s4, 3
	s_nop 0
	v_addc_co_u32_e32 v91, vcc, 0, v65, vcc
	s_ashr_i32 s1, s0, 31
	s_lshl_b64 s[0:1], s[0:1], 11
	v_lshl_add_u64 v[106:107], v[6:7], 0, s[0:1]
	s_mov_b32 s17, s11
	global_load_dwordx2 v[82:83], v[64:65], off offset:512
	global_load_dwordx2 v[202:203], v[0:1], off offset:512
	global_load_dwordx2 v[84:85], v[64:65], off offset:1024
	global_load_dwordx2 v[204:205], v[0:1], off offset:1024
	global_load_dwordx2 v[86:87], v[64:65], off offset:1536
	global_load_dwordx2 v[32:33], v[0:1], off offset:1536
	global_load_dwordx2 v[96:97], v[64:65], off offset:2048
	global_load_dwordx2 v[44:45], v[40:41], off
	global_load_dwordx2 v[126:127], v[64:65], off offset:2560
	global_load_dwordx2 v[206:207], v[40:41], off offset:512
	global_load_dwordx2 v[128:129], v[64:65], off offset:3072
	global_load_dwordx2 v[220:221], v[40:41], off offset:1024
	global_load_dwordx2 v[140:141], v[64:65], off offset:3584
	global_load_dwordx2 v[46:47], v[40:41], off offset:1536
	global_load_dwordx2 v[98:99], v[90:91], off
	global_load_dwordx2 v[64:65], v[88:89], off
	global_load_dwordx2 v[100:101], v[90:91], off offset:512
	global_load_dwordx2 v[222:223], v[88:89], off offset:512
	global_load_dwordx2 v[142:143], v[90:91], off offset:1024
	global_load_dwordx2 v[224:225], v[88:89], off offset:1024
	global_load_dwordx2 v[148:149], v[90:91], off offset:1536
	global_load_dwordx2 v[76:77], v[88:89], off offset:1536
	global_load_dwordx2 v[150:151], v[90:91], off offset:2048
	global_load_dwordx2 v[78:79], v[106:107], off
	global_load_dwordx2 v[152:153], v[90:91], off offset:2560
	global_load_dwordx2 v[92:93], v[106:107], off offset:512
	global_load_dwordx2 v[160:161], v[90:91], off offset:3072
	global_load_dwordx2 v[226:227], v[106:107], off offset:1024
	global_load_dwordx2 v[174:175], v[90:91], off offset:3584
	global_load_dwordx2 v[90:91], v[106:107], off offset:1536
	global_load_dwordx4 v[228:231], v190, s[98:99]
	global_load_dwordx4 v[198:201], v[10:11], off
	global_load_dwordx4 v[232:235], v191, s[98:99]
	global_load_dwordx4 v[236:239], v[12:13], off
	global_load_dwordx4 v[240:243], v192, s[98:99]
	global_load_dwordx4 v[244:247], v[14:15], off
	global_load_dwordx4 v[212:215], v193, s[98:99]
	global_load_dwordx4 v[216:219], v[16:17], off
	s_waitcnt vmcnt(0)
	v_lshlrev_b32_e32 v48, 16, v2
	v_and_b32_e32 v49, 0xffff0000, v2
	v_lshlrev_b32_e32 v50, 16, v3
	v_and_b32_e32 v51, 0xffff0000, v3
	v_lshlrev_b32_e32 v38, 16, v202
	v_and_b32_e32 v39, 0xffff0000, v202
	v_lshlrev_b32_e32 v42, 16, v203
	v_and_b32_e32 v43, 0xffff0000, v203
	v_lshlrev_b32_e32 v132, 16, v84
	v_and_b32_e32 v133, 0xffff0000, v84
	v_lshlrev_b32_e32 v134, 16, v85
	v_lshlrev_b32_e32 v60, 16, v44
	v_and_b32_e32 v61, 0xffff0000, v44
	v_lshlrev_b32_e32 v62, 16, v45
	v_and_b32_e32 v63, 0xffff0000, v45
	v_and_b32_e32 v135, 0xffff0000, v85
	v_lshlrev_b32_e32 v121, 16, v86
	v_and_b32_e32 v119, 0xffff0000, v86
	v_mul_f32_e32 v118, v119, v119
	v_lshlrev_b32_e32 v34, 16, v204
	v_and_b32_e32 v35, 0xffff0000, v204
	v_lshlrev_b32_e32 v36, 16, v205
	v_and_b32_e32 v37, 0xffff0000, v205
	v_lshlrev_b32_e32 v2, 16, v32
	v_and_b32_e32 v3, 0xffff0000, v32
	v_lshlrev_b32_e32 v32, 16, v33
	v_and_b32_e32 v33, 0xffff0000, v33
	v_lshlrev_b32_e32 v56, 16, v206
	v_and_b32_e32 v57, 0xffff0000, v206
	v_lshlrev_b32_e32 v58, 16, v207
	v_and_b32_e32 v59, 0xffff0000, v207
	s_nop 0
	v_lshlrev_b32_e32 v138, 16, v129
	v_and_b32_e32 v139, 0xffff0000, v129
	v_and_b32_e32 v129, 0xffff0000, v140
	v_lshlrev_b32_e32 v72, 16, v64
	v_and_b32_e32 v73, 0xffff0000, v64
	v_lshlrev_b32_e32 v74, 16, v65
	v_and_b32_e32 v75, 0xffff0000, v65
	v_lshlrev_b32_e32 v176, 16, v98
	v_and_b32_e32 v177, 0xffff0000, v98
	v_lshlrev_b32_e32 v98, 16, v99
	v_and_b32_e32 v99, 0xffff0000, v99
	v_lshlrev_b32_e32 v52, 16, v220
	v_and_b32_e32 v53, 0xffff0000, v220
	v_lshlrev_b32_e32 v54, 16, v221
	v_and_b32_e32 v55, 0xffff0000, v221
	v_lshlrev_b32_e32 v44, 16, v46
	v_and_b32_e32 v45, 0xffff0000, v46
	v_lshlrev_b32_e32 v46, 16, v47
	v_and_b32_e32 v47, 0xffff0000, v47
	v_and_b32_e32 v165, 0xffff0000, v101
	v_lshlrev_b32_e32 v66, 16, v222
	v_and_b32_e32 v67, 0xffff0000, v222
	v_lshlrev_b32_e32 v68, 16, v223
	v_and_b32_e32 v69, 0xffff0000, v223
	v_and_b32_e32 v164, 0xffff0000, v100
	v_lshlrev_b32_e32 v163, 16, v101
	v_lshlrev_b32_e32 v162, 16, v100
	v_pk_mul_f32 v[100:101], v[164:165], v[164:165]
	v_lshlrev_b32_e32 v70, 16, v224
	v_pk_fma_f32 v[100:101], v[162:163], v[162:163], v[100:101]
	v_and_b32_e32 v181, 0xffff0000, v151
	v_lshlrev_b32_e32 v122, 16, v92
	v_and_b32_e32 v123, 0xffff0000, v92
	v_lshlrev_b32_e32 v124, 16, v93
	v_and_b32_e32 v125, 0xffff0000, v93
	s_nop 0
	v_pk_add_f32 v[100:101], v[100:101], v[100:101] op_sel:[0,1] op_sel_hi:[1,0]
	v_and_b32_e32 v179, 0xffff0000, v150
	v_lshlrev_b32_e32 v180, 16, v151
	v_and_b32_e32 v173, 0xffff0000, v153
	v_lshlrev_b32_e32 v178, 16, v150
	v_lshlrev_b32_e32 v102, 16, v76
	v_and_b32_e32 v103, 0xffff0000, v76
	v_lshlrev_b32_e32 v104, 16, v77
	v_and_b32_e32 v105, 0xffff0000, v77
	v_lshlrev_b32_e32 v76, 16, v78
	v_and_b32_e32 v77, 0xffff0000, v78
	v_lshlrev_b32_e32 v78, 16, v79
	v_and_b32_e32 v79, 0xffff0000, v79
	v_and_b32_e32 v71, 0xffff0000, v224
	v_lshlrev_b32_e32 v64, 16, v225
	v_and_b32_e32 v65, 0xffff0000, v225
	v_and_b32_e32 v151, 0xffff0000, v174
	v_lshlrev_b32_e32 v114, 16, v227
	v_and_b32_e32 v115, 0xffff0000, v227
	v_and_b32_e32 v93, 0xffff0000, v81
	v_lshlrev_b32_e32 v112, 16, v226
	v_and_b32_e32 v113, 0xffff0000, v226
	v_lshlrev_b32_e32 v108, 16, v90
	v_and_b32_e32 v109, 0xffff0000, v90
	v_lshlrev_b32_e32 v110, 16, v91
	v_and_b32_e32 v111, 0xffff0000, v91
	v_lshlrev_b32_e32 v90, 16, v80
	v_and_b32_e32 v91, 0xffff0000, v80
	v_lshlrev_b32_e32 v92, 16, v81
	v_mul_f32_e32 v80, v93, v93
	v_pk_fma_f32 v[94:95], v[92:93], v[92:93], v[80:81] op_sel_hi:[1,1,0]
	v_lshlrev_b32_e32 v81, 16, v83
	v_lshlrev_b32_e32 v80, 16, v82
	v_and_b32_e32 v83, 0xffff0000, v83
	v_and_b32_e32 v82, 0xffff0000, v82
	v_mul_f32_e32 v84, v91, v91
	v_pk_mul_f32 v[116:117], v[82:83], v[82:83]
	v_pk_fma_f32 v[84:85], v[90:91], v[90:91], v[84:85] op_sel_hi:[1,1,0]
	v_pk_fma_f32 v[130:131], v[80:81], v[80:81], v[116:117]
	v_lshlrev_b32_e32 v116, 16, v87
	v_and_b32_e32 v117, 0xffff0000, v87
	v_mov_b32_e32 v120, v84
	v_mov_b32_e32 v86, v94
	v_mov_b32_e32 v87, v121
	v_pk_add_f32 v[84:85], v[84:85], v[94:95]
	v_pk_mul_f32 v[86:87], v[120:121], v[86:87]
	v_mul_f32_e32 v94, v135, v135
	v_mov_b32_e32 v85, v87
	v_pk_add_f32 v[86:87], v[130:131], v[130:131] op_sel:[0,1] op_sel_hi:[1,0]
	v_mul_f32_e32 v136, v116, v116
	v_mov_b32_e32 v87, v118
	v_pk_add_f32 v[84:85], v[84:85], v[86:87]
	v_mul_f32_e32 v86, v133, v133
	v_mul_f32_e32 v137, v117, v117
	v_pk_fma_f32 v[86:87], v[132:133], v[132:133], v[86:87] op_sel_hi:[1,1,0]
	v_pk_fma_f32 v[94:95], v[134:135], v[134:135], v[94:95] op_sel_hi:[1,1,0]
	v_mov_b32_e32 v87, v136
	v_mov_b32_e32 v95, v137
	v_pk_add_f32 v[86:87], v[86:87], v[94:95]
	v_lshlrev_b32_e32 v94, 16, v96
	v_and_b32_e32 v95, 0xffff0000, v96
	v_lshlrev_b32_e32 v96, 16, v97
	v_and_b32_e32 v97, 0xffff0000, v97
	v_pk_add_f32 v[144:145], v[84:85], v[86:87]
	v_mul_f32_e32 v84, v97, v97
	v_and_b32_e32 v87, 0xffff0000, v127
	v_and_b32_e32 v86, 0xffff0000, v126
	v_pk_fma_f32 v[146:147], v[96:97], v[96:97], v[84:85] op_sel_hi:[1,1,0]
	v_lshlrev_b32_e32 v85, 16, v127
	v_lshlrev_b32_e32 v84, 16, v126
	v_pk_mul_f32 v[126:127], v[86:87], v[86:87]
	v_mul_f32_e32 v118, v95, v95
	v_pk_fma_f32 v[154:155], v[84:85], v[84:85], v[126:127]
	v_lshlrev_b32_e32 v131, 16, v140
	v_lshlrev_b32_e32 v126, 16, v141
	v_and_b32_e32 v127, 0xffff0000, v141
	v_pk_fma_f32 v[140:141], v[94:95], v[94:95], v[118:119] op_sel_hi:[1,1,0]
	v_mov_b32_e32 v156, v146
	v_mov_b32_e32 v130, v140
	v_mov_b32_e32 v157, v131
	v_pk_add_f32 v[140:141], v[140:141], v[146:147]
	v_pk_mul_f32 v[146:147], v[130:131], v[156:157]
	v_and_b32_e32 v137, 0xffff0000, v128
	v_mul_f32_e32 v120, v129, v129
	v_mov_b32_e32 v141, v147
	v_pk_add_f32 v[146:147], v[154:155], v[154:155] op_sel:[0,1] op_sel_hi:[1,0]
	v_lshlrev_b32_e32 v136, 16, v128
	v_mov_b32_e32 v147, v120
	v_mul_f32_e32 v118, v137, v137
	v_pk_add_f32 v[140:141], v[140:141], v[146:147]
	v_pk_fma_f32 v[146:147], v[136:137], v[136:137], v[118:119] op_sel_hi:[1,1,0]
	v_mul_f32_e32 v118, v139, v139
	v_mul_f32_e32 v128, v126, v126
	v_mul_f32_e32 v158, v127, v127
	v_pk_fma_f32 v[154:155], v[138:139], v[138:139], v[118:119] op_sel_hi:[1,1,0]
	v_mov_b32_e32 v147, v128
	v_mov_b32_e32 v155, v158
	v_pk_add_f32 v[146:147], v[146:147], v[154:155]
	v_lshlrev_b32_e32 v154, 16, v142
	v_pk_add_f32 v[140:141], v[140:141], v[146:147]
	v_mov_b32_e32 v147, v144
	v_mov_b32_e32 v146, v140
	v_mov_b32_e32 v144, v141
	v_pk_add_f32 v[140:141], v[146:147], v[144:145]
	ds_bpermute_b32 v145, v184, v141
	ds_bpermute_b32 v144, v184, v140
	v_and_b32_e32 v155, 0xffff0000, v142
	v_lshlrev_b32_e32 v156, 16, v143
	v_and_b32_e32 v157, 0xffff0000, v143
	v_lshlrev_b32_e32 v147, 16, v148
	s_waitcnt lgkmcnt(0)
	v_pk_add_f32 v[140:141], v[140:141], v[144:145]
	ds_bpermute_b32 v145, v185, v141
	ds_bpermute_b32 v144, v185, v140
	v_lshlrev_b32_e32 v142, 16, v149
	v_and_b32_e32 v143, 0xffff0000, v149
	v_mov_b32_e32 v167, v147
	v_mul_f32_e32 v172, v143, v143
	s_waitcnt lgkmcnt(0)
	v_pk_add_f32 v[140:141], v[140:141], v[144:145]
	ds_bpermute_b32 v145, v186, v141
	ds_bpermute_b32 v144, v186, v140
	s_waitcnt lgkmcnt(0)
	v_pk_add_f32 v[140:141], v[140:141], v[144:145]
	ds_bpermute_b32 v145, v187, v141
	ds_bpermute_b32 v144, v187, v140
	s_waitcnt lgkmcnt(0)
	v_pk_add_f32 v[140:141], v[140:141], v[144:145]
	ds_bpermute_b32 v145, v188, v141
	ds_bpermute_b32 v144, v188, v140
	s_waitcnt lgkmcnt(0)
	v_pk_add_f32 v[140:141], v[140:141], v[144:145]
	ds_bpermute_b32 v145, v189, v141
	ds_bpermute_b32 v144, v189, v140
	s_waitcnt lgkmcnt(0)
	v_pk_add_f32 v[144:145], v[140:141], v[144:145]
	v_mov_b64_e32 v[140:141], s[8:9]
	v_pk_fma_f32 v[144:145], v[144:145], s[6:7], v[140:141] op_sel_hi:[1,0,0]
	s_nop 0
	v_mul_f32_e32 v118, 0x4b800000, v145
	v_cmp_gt_f32_e64 s[0:1], s21, v145
	v_cmp_gt_f32_e32 vcc, s21, v144
	s_nop 0
	v_cndmask_b32_e64 v118, v145, v118, s[0:1]
	v_rsq_f32_e32 v118, v118
	v_and_b32_e32 v145, 0xffff0000, v148
	v_mul_f32_e32 v130, v145, v145
	v_mov_b32_e32 v101, v130
	v_mul_f32_e32 v120, 0x45800000, v118
	v_cndmask_b32_e64 v128, v118, v120, s[0:1]
	v_mul_f32_e32 v118, 0x4b800000, v144
	v_cndmask_b32_e32 v118, v144, v118, vcc
	v_rsq_f32_e32 v118, v118
	v_mul_f32_e32 v144, v142, v142
	v_mul_f32_e32 v130, v151, v151
	v_pk_mul_f32 v[90:91], v[128:129], v[90:91] op_sel_hi:[0,1]
	v_mul_f32_e32 v120, 0x45800000, v118
	v_cndmask_b32_e32 v120, v118, v120, vcc
	v_mul_f32_e32 v118, v99, v99
	v_pk_fma_f32 v[158:159], v[98:99], v[98:99], v[118:119] op_sel_hi:[1,1,0]
	v_mul_f32_e32 v118, v177, v177
	v_pk_fma_f32 v[148:149], v[176:177], v[176:177], v[118:119] op_sel_hi:[1,1,0]
	v_mov_b32_e32 v166, v158
	v_mov_b32_e32 v146, v148
	v_pk_add_f32 v[148:149], v[148:149], v[158:159]
	v_pk_mul_f32 v[158:159], v[146:147], v[166:167]
	v_mul_f32_e32 v118, v155, v155
	v_mov_b32_e32 v149, v159
	v_pk_add_f32 v[100:101], v[148:149], v[100:101]
	v_pk_fma_f32 v[148:149], v[154:155], v[154:155], v[118:119] op_sel_hi:[1,1,0]
	v_mul_f32_e32 v118, v157, v157
	v_pk_fma_f32 v[158:159], v[156:157], v[156:157], v[118:119] op_sel_hi:[1,1,0]
	v_mov_b32_e32 v149, v144
	v_mov_b32_e32 v159, v172
	v_pk_add_f32 v[148:149], v[148:149], v[158:159]
	v_mul_f32_e32 v118, v181, v181
	v_and_b32_e32 v172, 0xffff0000, v152
	v_pk_add_f32 v[100:101], v[100:101], v[148:149]
	v_pk_fma_f32 v[182:183], v[180:181], v[180:181], v[118:119] op_sel_hi:[1,1,0]
	v_lshlrev_b32_e32 v167, 16, v153
	v_lshlrev_b32_e32 v166, 16, v152
	v_pk_mul_f32 v[148:149], v[172:173], v[172:173]
	v_mul_f32_e32 v118, v179, v179
	v_pk_fma_f32 v[194:195], v[166:167], v[166:167], v[148:149]
	v_lshlrev_b32_e32 v153, 16, v174
	v_lshlrev_b32_e32 v148, 16, v175
	v_and_b32_e32 v149, 0xffff0000, v175
	v_pk_fma_f32 v[174:175], v[178:179], v[178:179], v[118:119] op_sel_hi:[1,1,0]
	v_mov_b32_e32 v196, v182
	v_mov_b32_e32 v152, v174
	v_mov_b32_e32 v197, v153
	v_pk_add_f32 v[174:175], v[174:175], v[182:183]
	v_pk_mul_f32 v[182:183], v[152:153], v[196:197]
	v_and_b32_e32 v159, 0xffff0000, v160
	v_mov_b32_e32 v175, v183
	v_pk_add_f32 v[182:183], v[194:195], v[194:195] op_sel:[0,1] op_sel_hi:[1,0]
	v_lshlrev_b32_e32 v158, 16, v160
	v_lshlrev_b32_e32 v160, 16, v161
	v_and_b32_e32 v161, 0xffff0000, v161
	v_mov_b32_e32 v183, v130
	v_mul_f32_e32 v118, v159, v159
	v_pk_add_f32 v[174:175], v[174:175], v[182:183]
	v_pk_fma_f32 v[182:183], v[158:159], v[158:159], v[118:119] op_sel_hi:[1,1,0]
	v_mul_f32_e32 v118, v161, v161
	v_mul_f32_e32 v144, v148, v148
	v_mul_f32_e32 v146, v149, v149
	v_pk_fma_f32 v[194:195], v[160:161], v[160:161], v[118:119] op_sel_hi:[1,1,0]
	v_mov_b32_e32 v183, v144
	v_mov_b32_e32 v195, v146
	v_pk_add_f32 v[182:183], v[182:183], v[194:195]
	v_pk_mul_f32 v[92:93], v[128:129], v[92:93] op_sel_hi:[0,1]
	v_pk_add_f32 v[174:175], v[174:175], v[182:183]
	v_mov_b32_e32 v183, v100
	v_mov_b32_e32 v182, v174
	v_mov_b32_e32 v100, v175
	v_pk_add_f32 v[100:101], v[182:183], v[100:101]
	ds_bpermute_b32 v175, v184, v101
	ds_bpermute_b32 v174, v184, v100
	v_mov_b32_e32 v144, v147
	v_mov_b32_e32 v150, v153
	s_waitcnt lgkmcnt(0)
	v_pk_add_f32 v[100:101], v[100:101], v[174:175]
	ds_bpermute_b32 v175, v185, v101
	ds_bpermute_b32 v174, v185, v100
	s_waitcnt lgkmcnt(0)
	v_pk_add_f32 v[100:101], v[100:101], v[174:175]
	ds_bpermute_b32 v175, v186, v101
	ds_bpermute_b32 v174, v186, v100
	s_waitcnt lgkmcnt(0)
	v_pk_add_f32 v[100:101], v[100:101], v[174:175]
	ds_bpermute_b32 v175, v187, v101
	ds_bpermute_b32 v174, v187, v100
	s_waitcnt lgkmcnt(0)
	v_pk_add_f32 v[100:101], v[100:101], v[174:175]
	ds_bpermute_b32 v175, v188, v101
	ds_bpermute_b32 v174, v188, v100
	s_waitcnt lgkmcnt(0)
	v_pk_add_f32 v[100:101], v[100:101], v[174:175]
	ds_bpermute_b32 v175, v189, v101
	ds_bpermute_b32 v174, v189, v100
	s_waitcnt lgkmcnt(0)
	v_pk_add_f32 v[100:101], v[100:101], v[174:175]
	s_nop 0
	v_pk_fma_f32 v[100:101], v[100:101], s[6:7], v[140:141] op_sel_hi:[1,0,0]
	s_nop 0
	v_mul_f32_e32 v118, 0x4b800000, v101
	v_cmp_gt_f32_e64 s[0:1], s21, v101
	v_cmp_gt_f32_e32 vcc, s21, v100
	s_nop 0
	v_cndmask_b32_e64 v101, v101, v118, s[0:1]
	v_rsq_f32_e32 v101, v101
	s_nop 0
	v_mul_f32_e32 v118, 0x45800000, v101
	v_cndmask_b32_e64 v146, v101, v118, s[0:1]
	s_ashr_i32 s0, s2, 11
	s_mul_i32 s0, s0, 9
	s_ashr_i32 s1, s0, 31
	s_lshl_b64 s[0:1], s[0:1], 12
	s_add_u32 s5, s14, s0
	s_addc_u32 s13, s15, s1
	s_add_u32 s0, s5, 0x5000
	s_addc_u32 s1, s13, 0
	v_mul_f32_e32 v101, 0x4b800000, v100
	v_cndmask_b32_e32 v100, v100, v101, vcc
	v_rsq_f32_e32 v100, v100
	v_mov_b32_e32 v118, v121
	v_mul_f32_e32 v101, 0x45800000, v100
	v_cndmask_b32_e32 v130, v100, v101, vcc
	v_pk_mul_f32 v[196:197], v[230:231], v[200:201]
	v_pk_mul_f32 v[194:195], v[228:229], v[198:199]
	v_pk_fma_f32 v[174:175], v[92:93], v[196:197], v[50:51]
	v_pk_fma_f32 v[182:183], v[90:91], v[194:195], v[48:49]
	v_cvt_pk_bf16_f32 v49, v174, v175
	v_cvt_pk_bf16_f32 v48, v182, v183
	global_store_dwordx2 v[0:1], v[48:49], off
	v_pk_mul_f32 v[48:49], v[174:175], v[174:175]
	v_pk_mul_f32 v[50:51], v[182:183], v[182:183]
	s_nop 0
	v_pk_mov_b32 v[90:91], v[50:51], v[48:49] op_sel:[1,0]
	v_mov_b32_e32 v51, v49
	v_pk_add_f32 v[198:199], v[90:91], v[50:51]
	v_pk_mul_f32 v[48:49], v[120:121], v[94:95] op_sel_hi:[0,1]
	v_pk_mul_f32 v[50:51], v[120:121], v[96:97] op_sel_hi:[0,1]
	v_pk_fma_f32 v[94:95], v[50:51], v[196:197], v[62:63]
	v_pk_fma_f32 v[96:97], v[48:49], v[194:195], v[60:61]
	v_cvt_pk_bf16_f32 v49, v94, v95
	v_cvt_pk_bf16_f32 v48, v96, v97
	global_store_dwordx2 v[40:41], v[48:49], off
	v_pk_mul_f32 v[48:49], v[94:95], v[94:95]
	v_pk_mul_f32 v[50:51], v[96:97], v[96:97]
	s_nop 0
	v_pk_mov_b32 v[60:61], v[50:51], v[48:49] op_sel:[1,0]
	v_mov_b32_e32 v51, v49
	v_pk_add_f32 v[200:201], v[60:61], v[50:51]
	v_pk_mul_f32 v[48:49], v[146:147], v[176:177] op_sel_hi:[0,1]
	v_pk_mul_f32 v[50:51], v[146:147], v[98:99] op_sel_hi:[0,1]
	v_pk_fma_f32 v[98:99], v[196:197], v[50:51], v[74:75]
	v_pk_fma_f32 v[100:101], v[194:195], v[48:49], v[72:73]
	v_cvt_pk_bf16_f32 v49, v98, v99
	v_cvt_pk_bf16_f32 v48, v100, v101
	global_store_dwordx2 v[88:89], v[48:49], off
	v_pk_mul_f32 v[48:49], v[98:99], v[98:99]
	v_pk_mul_f32 v[50:51], v[100:101], v[100:101]
	s_nop 0
	v_pk_mov_b32 v[60:61], v[50:51], v[48:49] op_sel:[1,0]
	v_mov_b32_e32 v51, v49
	v_pk_add_f32 v[176:177], v[60:61], v[50:51]
	v_pk_mul_f32 v[48:49], v[130:131], v[178:179] op_sel_hi:[0,1]
	v_pk_mul_f32 v[50:51], v[130:131], v[180:181] op_sel_hi:[0,1]
	v_pk_fma_f32 v[90:91], v[196:197], v[50:51], v[78:79]
	v_pk_fma_f32 v[92:93], v[194:195], v[48:49], v[76:77]
	v_cvt_pk_bf16_f32 v49, v90, v91
	v_cvt_pk_bf16_f32 v48, v92, v93
	global_store_dwordx2 v[106:107], v[48:49], off
	v_pk_mul_f32 v[48:49], v[90:91], v[90:91]
	v_pk_mul_f32 v[50:51], v[92:93], v[92:93]
	s_nop 0
	v_pk_mov_b32 v[60:61], v[50:51], v[48:49] op_sel:[1,0]
	v_mov_b32_e32 v51, v49
	v_pk_add_f32 v[178:179], v[60:61], v[50:51]
	v_pk_mul_f32 v[48:49], v[232:233], v[236:237]
	v_mov_b32_e32 v60, v80
	v_mov_b32_e32 v61, v82
	v_mov_b32_e32 v82, v81
	v_pk_mul_f32 v[50:51], v[234:235], v[238:239]
	v_pk_mul_f32 v[60:61], v[128:129], v[60:61] op_sel_hi:[0,1]
	v_pk_mul_f32 v[62:63], v[128:129], v[82:83] op_sel_hi:[0,1]
	v_pk_fma_f32 v[76:77], v[62:63], v[50:51], v[42:43]
	v_pk_fma_f32 v[78:79], v[60:61], v[48:49], v[38:39]
	v_cvt_pk_bf16_f32 v39, v76, v77
	v_cvt_pk_bf16_f32 v38, v78, v79
	global_store_dwordx2 v[0:1], v[38:39], off offset:512
	v_pk_mul_f32 v[38:39], v[78:79], v[78:79]
	v_pk_mul_f32 v[42:43], v[76:77], v[76:77]
	s_nop 0
	v_pk_mov_b32 v[60:61], v[38:39], v[42:43] op_sel:[1,0]
	v_mov_b32_e32 v39, v43
	v_mov_b32_e32 v42, v84
	v_mov_b32_e32 v43, v86
	v_mov_b32_e32 v86, v85
	v_pk_add_f32 v[38:39], v[60:61], v[38:39]
	v_pk_mul_f32 v[42:43], v[120:121], v[42:43] op_sel_hi:[0,1]
	v_pk_mul_f32 v[60:61], v[120:121], v[86:87] op_sel_hi:[0,1]
	v_pk_fma_f32 v[80:81], v[60:61], v[50:51], v[58:59]
	v_pk_fma_f32 v[82:83], v[42:43], v[48:49], v[56:57]
	v_cvt_pk_bf16_f32 v43, v80, v81
	v_cvt_pk_bf16_f32 v42, v82, v83
	global_store_dwordx2 v[40:41], v[42:43], off offset:512
	v_pk_mul_f32 v[42:43], v[82:83], v[82:83]
	v_pk_mul_f32 v[56:57], v[80:81], v[80:81]
	s_nop 0
	v_pk_mov_b32 v[58:59], v[42:43], v[56:57] op_sel:[1,0]
	v_mov_b32_e32 v43, v57
	v_mov_b32_e32 v56, v162
	v_mov_b32_e32 v57, v164
	v_mov_b32_e32 v164, v163
	v_pk_add_f32 v[42:43], v[58:59], v[42:43]
	v_pk_mul_f32 v[56:57], v[146:147], v[56:57] op_sel_hi:[0,1]
	v_pk_mul_f32 v[58:59], v[146:147], v[164:165] op_sel_hi:[0,1]
	v_pk_fma_f32 v[84:85], v[58:59], v[50:51], v[68:69]
	v_pk_fma_f32 v[86:87], v[56:57], v[48:49], v[66:67]
	v_cvt_pk_bf16_f32 v57, v84, v85
	v_cvt_pk_bf16_f32 v56, v86, v87
	global_store_dwordx2 v[88:89], v[56:57], off offset:512
	v_pk_mul_f32 v[56:57], v[86:87], v[86:87]
	v_pk_mul_f32 v[58:59], v[84:85], v[84:85]
	s_nop 0
	v_pk_mov_b32 v[60:61], v[56:57], v[58:59] op_sel:[1,0]
	v_mov_b32_e32 v57, v59
	v_pk_add_f32 v[162:163], v[60:61], v[56:57]
	v_mov_b32_e32 v56, v166
	v_mov_b32_e32 v57, v172
	v_mov_b32_e32 v172, v167
	v_pk_mul_f32 v[56:57], v[130:131], v[56:57] op_sel_hi:[0,1]
	v_pk_mul_f32 v[58:59], v[130:131], v[172:173] op_sel_hi:[0,1]
	v_pk_fma_f32 v[72:73], v[50:51], v[58:59], v[124:125]
	v_pk_fma_f32 v[74:75], v[48:49], v[56:57], v[122:123]
	v_cvt_pk_bf16_f32 v49, v72, v73
	v_cvt_pk_bf16_f32 v48, v74, v75
	global_store_dwordx2 v[106:107], v[48:49], off offset:512
	v_pk_mul_f32 v[48:49], v[74:75], v[74:75]
	v_pk_mul_f32 v[50:51], v[72:73], v[72:73]
	s_nop 0
	v_pk_mov_b32 v[56:57], v[48:49], v[50:51] op_sel:[1,0]
	v_mov_b32_e32 v49, v51
	v_pk_add_f32 v[122:123], v[56:57], v[48:49]
	v_pk_mul_f32 v[50:51], v[242:243], v[246:247]
	v_pk_mul_f32 v[48:49], v[240:241], v[244:245]
	v_pk_mul_f32 v[56:57], v[128:129], v[132:133] op_sel_hi:[0,1]
	v_pk_mul_f32 v[58:59], v[128:129], v[134:135] op_sel_hi:[0,1]
	v_pk_fma_f32 v[60:61], v[58:59], v[50:51], v[36:37]
	v_pk_fma_f32 v[66:67], v[56:57], v[48:49], v[34:35]
	v_cvt_pk_bf16_f32 v35, v60, v61
	v_cvt_pk_bf16_f32 v34, v66, v67
	global_store_dwordx2 v[0:1], v[34:35], off offset:1024
	v_pk_mul_f32 v[34:35], v[120:121], v[136:137] op_sel_hi:[0,1]
	v_pk_mul_f32 v[36:37], v[120:121], v[138:139] op_sel_hi:[0,1]
	v_pk_fma_f32 v[62:63], v[36:37], v[50:51], v[54:55]
	v_pk_fma_f32 v[68:69], v[34:35], v[48:49], v[52:53]
	v_cvt_pk_bf16_f32 v35, v62, v63
	v_cvt_pk_bf16_f32 v34, v68, v69
	global_store_dwordx2 v[40:41], v[34:35], off offset:1024
	v_pk_mul_f32 v[34:35], v[146:147], v[154:155] op_sel_hi:[0,1]
	v_pk_mul_f32 v[36:37], v[146:147], v[156:157] op_sel_hi:[0,1]
	v_pk_fma_f32 v[64:65], v[36:37], v[50:51], v[64:65]
	v_pk_fma_f32 v[70:71], v[34:35], v[48:49], v[70:71]
	v_cvt_pk_bf16_f32 v35, v64, v65
	v_cvt_pk_bf16_f32 v34, v70, v71
	global_store_dwordx2 v[88:89], v[34:35], off offset:1024
	v_pk_mul_f32 v[34:35], v[130:131], v[158:159] op_sel_hi:[0,1]
	v_pk_mul_f32 v[36:37], v[130:131], v[160:161] op_sel_hi:[0,1]
	v_pk_fma_f32 v[56:57], v[36:37], v[50:51], v[114:115]
	v_pk_fma_f32 v[58:59], v[34:35], v[48:49], v[112:113]
	v_cvt_pk_bf16_f32 v35, v56, v57
	v_cvt_pk_bf16_f32 v34, v58, v59
	global_store_dwordx2 v[106:107], v[34:35], off offset:1024
	s_nop 0
	v_pk_mul_f32 v[50:51], v[214:215], v[218:219]
	v_pk_mul_f32 v[48:49], v[212:213], v[216:217]
	v_pk_mul_f32 v[34:35], v[128:129], v[118:119] op_sel_hi:[0,1]
	v_pk_mul_f32 v[36:37], v[128:129], v[116:117] op_sel_hi:[0,1]
	v_pk_fma_f32 v[32:33], v[36:37], v[50:51], v[32:33]
	v_pk_fma_f32 v[34:35], v[34:35], v[48:49], v[2:3]
	v_cvt_pk_bf16_f32 v3, v32, v33
	v_cvt_pk_bf16_f32 v2, v34, v35
	global_store_dwordx2 v[0:1], v[2:3], off offset:1536
	v_mul_f32_e32 v2, v34, v34
	v_pk_add_f32 v[0:1], v[198:199], v[198:199] op_sel:[0,1] op_sel_hi:[1,0]
	v_mul_f32_e32 v36, v35, v35
	v_mov_b32_e32 v1, v2
	v_pk_add_f32 v[2:3], v[38:39], v[38:39] op_sel:[0,1] op_sel_hi:[1,0]
	v_mul_f32_e32 v37, v32, v32
	v_mov_b32_e32 v3, v36
	v_pk_add_f32 v[0:1], v[0:1], v[2:3]
	v_mul_f32_e32 v2, v67, v67
	v_pk_fma_f32 v[2:3], v[66:67], v[66:67], v[2:3] op_sel_hi:[1,1,0]
	v_mul_f32_e32 v36, v61, v61
	v_mul_f32_e32 v52, v33, v33
	v_mov_b32_e32 v3, v37
	v_pk_fma_f32 v[36:37], v[60:61], v[60:61], v[36:37] op_sel_hi:[1,1,0]
	v_mov_b32_e32 v128, v131
	v_mov_b32_e32 v37, v52
	v_pk_add_f32 v[2:3], v[2:3], v[36:37]
	v_pk_mul_f32 v[36:37], v[120:121], v[126:127] op_sel_hi:[0,1]
	v_pk_add_f32 v[0:1], v[0:1], v[2:3]
	v_pk_mul_f32 v[2:3], v[120:121], v[128:129] op_sel_hi:[0,1]
	v_pk_fma_f32 v[36:37], v[36:37], v[50:51], v[46:47]
	v_pk_fma_f32 v[38:39], v[2:3], v[48:49], v[44:45]
	v_cvt_pk_bf16_f32 v3, v36, v37
	v_cvt_pk_bf16_f32 v2, v38, v39
	global_store_dwordx2 v[40:41], v[2:3], off offset:1536
	v_mul_f32_e32 v40, v38, v38
	v_pk_add_f32 v[2:3], v[200:201], v[200:201] op_sel:[0,1] op_sel_hi:[1,0]
	v_mul_f32_e32 v44, v39, v39
	v_mov_b32_e32 v3, v40
	v_pk_add_f32 v[40:41], v[42:43], v[42:43] op_sel:[0,1] op_sel_hi:[1,0]
	v_mul_f32_e32 v42, v63, v63
	v_mov_b32_e32 v41, v44
	v_pk_add_f32 v[2:3], v[2:3], v[40:41]
	v_mul_f32_e32 v40, v69, v69
	v_mul_f32_e32 v45, v36, v36
	v_mul_f32_e32 v46, v37, v37
	v_pk_fma_f32 v[40:41], v[68:69], v[68:69], v[40:41] op_sel_hi:[1,1,0]
	v_pk_fma_f32 v[42:43], v[62:63], v[62:63], v[42:43] op_sel_hi:[1,1,0]
	v_mov_b32_e32 v41, v45
	v_mov_b32_e32 v43, v46
	v_pk_add_f32 v[40:41], v[40:41], v[42:43]
	v_pk_mul_f32 v[42:43], v[146:147], v[144:145] op_sel_hi:[0,1]
	v_pk_add_f32 v[2:3], v[2:3], v[40:41]
	v_pk_mul_f32 v[40:41], v[146:147], v[142:143] op_sel_hi:[0,1]
	v_pk_fma_f32 v[40:41], v[40:41], v[50:51], v[104:105]
	v_pk_fma_f32 v[42:43], v[42:43], v[48:49], v[102:103]
	v_cvt_pk_bf16_f32 v45, v40, v41
	v_cvt_pk_bf16_f32 v44, v42, v43
	global_store_dwordx2 v[88:89], v[44:45], off offset:1536
	v_mul_f32_e32 v46, v42, v42
	v_pk_add_f32 v[44:45], v[176:177], v[176:177] op_sel:[0,1] op_sel_hi:[1,0]
	v_mul_f32_e32 v52, v43, v43
	v_mov_b32_e32 v45, v46
	v_pk_add_f32 v[46:47], v[162:163], v[162:163] op_sel:[0,1] op_sel_hi:[1,0]
	v_mul_f32_e32 v53, v40, v40
	v_mov_b32_e32 v47, v52
	v_pk_add_f32 v[44:45], v[44:45], v[46:47]
	v_mul_f32_e32 v46, v71, v71
	v_pk_fma_f32 v[46:47], v[70:71], v[70:71], v[46:47] op_sel_hi:[1,1,0]
	v_mul_f32_e32 v52, v65, v65
	v_mul_f32_e32 v54, v41, v41
	v_mov_b32_e32 v47, v53
	v_pk_fma_f32 v[52:53], v[64:65], v[64:65], v[52:53] op_sel_hi:[1,1,0]
	s_nop 0
	v_mov_b32_e32 v53, v54
	v_pk_add_f32 v[46:47], v[46:47], v[52:53]
	s_nop 0
	v_pk_add_f32 v[52:53], v[44:45], v[46:47]
	v_pk_mul_f32 v[46:47], v[130:131], v[150:151] op_sel_hi:[0,1]
	v_pk_mul_f32 v[44:45], v[130:131], v[148:149] op_sel_hi:[0,1]
	v_pk_fma_f32 v[44:45], v[44:45], v[50:51], v[110:111]
	v_pk_fma_f32 v[46:47], v[46:47], v[48:49], v[108:109]
	v_cvt_pk_bf16_f32 v49, v44, v45
	v_cvt_pk_bf16_f32 v48, v46, v47
	global_store_dwordx2 v[106:107], v[48:49], off offset:1536
	v_mul_f32_e32 v50, v46, v46
	v_pk_add_f32 v[48:49], v[178:179], v[178:179] op_sel:[0,1] op_sel_hi:[1,0]
	v_mul_f32_e32 v54, v47, v47
	v_mov_b32_e32 v49, v50
	v_pk_add_f32 v[50:51], v[122:123], v[122:123] op_sel:[0,1] op_sel_hi:[1,0]
	v_mul_f32_e32 v55, v44, v44
	v_mov_b32_e32 v51, v54
	v_pk_add_f32 v[48:49], v[48:49], v[50:51]
	v_mul_f32_e32 v50, v59, v59
	v_pk_fma_f32 v[50:51], v[58:59], v[58:59], v[50:51] op_sel_hi:[1,1,0]
	v_mul_f32_e32 v54, v57, v57
	v_mul_f32_e32 v88, v45, v45
	v_mov_b32_e32 v51, v55
	v_pk_fma_f32 v[54:55], v[56:57], v[56:57], v[54:55] op_sel_hi:[1,1,0]
	s_nop 0
	v_mov_b32_e32 v55, v88
	v_pk_add_f32 v[50:51], v[50:51], v[54:55]
	s_nop 0
	v_pk_add_f32 v[54:55], v[48:49], v[50:51]
	v_mov_b32_e32 v48, v2
	v_mov_b32_e32 v49, v0
	v_mov_b32_e32 v0, v3
	v_pk_add_f32 v[0:1], v[48:49], v[0:1]
	ds_bpermute_b32 v3, v184, v1
	ds_bpermute_b32 v2, v184, v0
	s_waitcnt lgkmcnt(0)
	v_pk_add_f32 v[0:1], v[0:1], v[2:3]
	ds_bpermute_b32 v3, v185, v1
	ds_bpermute_b32 v2, v185, v0
	s_waitcnt lgkmcnt(0)
	v_pk_add_f32 v[0:1], v[0:1], v[2:3]
	ds_bpermute_b32 v3, v186, v1
	ds_bpermute_b32 v2, v186, v0
	s_waitcnt lgkmcnt(0)
	v_pk_add_f32 v[0:1], v[0:1], v[2:3]
	ds_bpermute_b32 v3, v187, v1
	ds_bpermute_b32 v2, v187, v0
	s_waitcnt lgkmcnt(0)
	v_pk_add_f32 v[0:1], v[0:1], v[2:3]
	ds_bpermute_b32 v3, v188, v1
	ds_bpermute_b32 v2, v188, v0
	s_waitcnt lgkmcnt(0)
	v_pk_add_f32 v[0:1], v[0:1], v[2:3]
	ds_bpermute_b32 v3, v189, v1
	ds_bpermute_b32 v2, v189, v0
	s_waitcnt lgkmcnt(0)
	v_pk_add_f32 v[0:1], v[0:1], v[2:3]
	s_nop 0
	v_pk_fma_f32 v[0:1], v[0:1], s[6:7], v[140:141] op_sel_hi:[1,0,0]
	s_nop 0
	v_mul_f32_e32 v2, 0x4b800000, v1
	v_cmp_gt_f32_e64 s[0:1], s21, v1
	v_cmp_gt_f32_e32 vcc, s21, v0
	s_nop 0
	v_cndmask_b32_e64 v1, v1, v2, s[0:1]
	v_rsq_f32_e32 v1, v1
	s_nop 0
	v_mul_f32_e32 v2, 0x45800000, v1
	v_cndmask_b32_e64 v50, v1, v2, s[0:1]
	v_mul_f32_e32 v1, 0x4b800000, v0
	v_cndmask_b32_e32 v0, v0, v1, vcc
	v_rsq_f32_e32 v0, v0
	v_pk_mul_f32 v[78:79], v[78:79], v[50:51] op_sel_hi:[1,0]
	v_pk_mul_f32 v[76:77], v[76:77], v[50:51] op_sel_hi:[1,0]
	v_pk_mul_f32 v[66:67], v[66:67], v[50:51] op_sel_hi:[1,0]
	v_mul_f32_e32 v1, 0x45800000, v0
	v_cndmask_b32_e32 v48, v0, v1, vcc
	v_mov_b32_e32 v0, v54
	v_mov_b32_e32 v1, v52
	v_mov_b32_e32 v52, v55
	v_pk_add_f32 v[0:1], v[0:1], v[52:53]
	ds_bpermute_b32 v3, v184, v1
	ds_bpermute_b32 v2, v184, v0
	v_pk_mul_f32 v[96:97], v[96:97], v[48:49] op_sel_hi:[1,0]
	v_pk_mul_f32 v[94:95], v[94:95], v[48:49] op_sel_hi:[1,0]
	v_pk_mul_f32 v[60:61], v[60:61], v[50:51] op_sel_hi:[1,0]
	v_pk_mul_f32 v[62:63], v[62:63], v[48:49] op_sel_hi:[1,0]
	s_waitcnt lgkmcnt(0)
	v_pk_add_f32 v[0:1], v[0:1], v[2:3]
	ds_bpermute_b32 v3, v185, v1
	ds_bpermute_b32 v2, v185, v0
	v_pk_mul_f32 v[34:35], v[34:35], v[50:51] op_sel_hi:[1,0]
	v_pk_mul_f32 v[32:33], v[32:33], v[50:51] op_sel_hi:[1,0]
	s_waitcnt lgkmcnt(0)
	v_pk_add_f32 v[0:1], v[0:1], v[2:3]
	ds_bpermute_b32 v3, v186, v1
	ds_bpermute_b32 v2, v186, v0
	s_waitcnt lgkmcnt(0)
	v_pk_add_f32 v[0:1], v[0:1], v[2:3]
	ds_bpermute_b32 v3, v187, v1
	ds_bpermute_b32 v2, v187, v0
	s_waitcnt lgkmcnt(0)
	v_pk_add_f32 v[0:1], v[0:1], v[2:3]
	ds_bpermute_b32 v3, v188, v1
	ds_bpermute_b32 v2, v188, v0
	s_waitcnt lgkmcnt(0)
	v_pk_add_f32 v[0:1], v[0:1], v[2:3]
	ds_bpermute_b32 v3, v189, v1
	ds_bpermute_b32 v2, v189, v0
	s_waitcnt lgkmcnt(0)
	v_pk_add_f32 v[0:1], v[0:1], v[2:3]
	s_nop 0
	v_pk_fma_f32 v[0:1], v[0:1], s[6:7], v[140:141] op_sel_hi:[1,0,0]
	s_nop 0
	v_mul_f32_e32 v2, 0x4b800000, v1
	v_cmp_gt_f32_e64 s[0:1], s21, v1
	v_cmp_gt_f32_e32 vcc, s21, v0
	s_nop 0
	v_cndmask_b32_e64 v1, v1, v2, s[0:1]
	v_rsq_f32_e32 v1, v1
	s_nop 0
	v_mul_f32_e32 v2, 0x45800000, v1
	v_cndmask_b32_e64 v54, v1, v2, s[0:1]
	v_mul_f32_e32 v1, 0x4b800000, v0
	v_cndmask_b32_e32 v0, v0, v1, vcc
	v_rsq_f32_e32 v0, v0
	s_add_u32 s0, s5, 0x6000
	s_addc_u32 s1, s13, 0
	s_add_u32 s12, s5, 0x7000
	v_mul_f32_e32 v1, 0x45800000, v0
	v_cndmask_b32_e32 v52, v0, v1, vcc
	s_addc_u32 s13, s13, 0
	global_load_dwordx4 v[104:107], v[18:19], off
	global_load_dwordx4 v[108:111], v190, s[12:13]
	global_load_dwordx4 v[0:3], v190, s[0:1]
	v_pk_mul_f32 v[92:93], v[92:93], v[52:53] op_sel_hi:[1,0]
	v_pk_mul_f32 v[90:91], v[90:91], v[52:53] op_sel_hi:[1,0]
	s_or_b32 s16, s10, 0x1000
	v_pk_mul_f32 v[74:75], v[74:75], v[52:53] op_sel_hi:[1,0]
	v_pk_mul_f32 v[72:73], v[72:73], v[52:53] op_sel_hi:[1,0]
	v_pk_mul_f32 v[58:59], v[58:59], v[52:53] op_sel_hi:[1,0]
	v_pk_mul_f32 v[56:57], v[56:57], v[52:53] op_sel_hi:[1,0]
	s_add_i32 s2, s2, s3
	s_add_i32 s7, s7, s9
	s_add_i32 s18, s18, s19
	s_add_i32 s4, s4, s20
	s_waitcnt vmcnt(1)
	v_pk_add_f32 v[88:89], v[110:111], 1.0 op_sel_hi:[1,0]
	v_pk_add_f32 v[108:109], v[108:109], 1.0 op_sel_hi:[1,0]
	v_pk_mul_f32 v[102:103], v[106:107], v[88:89]
	v_pk_mul_f32 v[104:105], v[104:105], v[108:109]
	v_pk_mul_f32 v[88:89], v[182:183], v[50:51] op_sel_hi:[1,0]
	v_pk_mul_f32 v[106:107], v[174:175], v[50:51] op_sel_hi:[1,0]
	s_waitcnt vmcnt(0)
	v_pk_fma_f32 v[88:89], v[88:89], v[104:105], v[0:1]
	v_pk_fma_f32 v[94:95], v[94:95], v[102:103], v[2:3]
	v_pk_fma_f32 v[96:97], v[96:97], v[104:105], v[0:1]
	v_pk_fma_f32 v[108:109], v[106:107], v[102:103], v[2:3]
	v_cvt_pk_bf16_f32 v106, v88, v89
	v_lshl_add_u64 v[88:89], v[8:9], 0, s[10:11]
	v_cvt_pk_bf16_f32 v96, v96, v97
	v_cvt_pk_bf16_f32 v97, v94, v95
	global_store_dwordx2 v[88:89], v[96:97], off offset:2048
	v_pk_mul_f32 v[94:95], v[100:101], v[54:55] op_sel_hi:[1,0]
	v_pk_mul_f32 v[96:97], v[98:99], v[54:55] op_sel_hi:[1,0]
	v_pk_fma_f32 v[94:95], v[104:105], v[94:95], v[0:1]
	v_pk_fma_f32 v[96:97], v[102:103], v[96:97], v[2:3]
	v_pk_fma_f32 v[2:3], v[102:103], v[90:91], v[2:3]
	v_pk_fma_f32 v[0:1], v[104:105], v[92:93], v[0:1]
	s_or_b32 s10, s10, 0x1800
	v_cvt_pk_bf16_f32 v107, v108, v109
	v_cvt_pk_bf16_f32 v94, v94, v95
	v_cvt_pk_bf16_f32 v95, v96, v97
	v_lshl_add_u64 v[96:97], v[8:9], 0, s[16:17]
	v_cvt_pk_bf16_f32 v0, v0, v1
	v_cvt_pk_bf16_f32 v1, v2, v3
	v_lshl_add_u64 v[2:3], v[8:9], 0, s[10:11]
	global_store_dwordx2 v[88:89], v[106:107], off
	global_store_dwordx2 v[96:97], v[94:95], off
	global_store_dwordx2 v[2:3], v[0:1], off
	global_load_dwordx4 v[0:3], v[20:21], off
	s_nop 0
	global_load_dwordx4 v[90:93], v191, s[12:13]
	global_load_dwordx4 v[94:97], v191, s[0:1]
	s_cmpk_lt_i32 s2, 0x4000
	s_waitcnt vmcnt(1)
	v_pk_add_f32 v[92:93], v[92:93], 1.0 op_sel_hi:[1,0]
	v_pk_add_f32 v[90:91], v[90:91], 1.0 op_sel_hi:[1,0]
	v_pk_mul_f32 v[2:3], v[2:3], v[92:93]
	v_pk_mul_f32 v[0:1], v[0:1], v[90:91]
	s_waitcnt vmcnt(0)
	v_pk_fma_f32 v[76:77], v[76:77], v[2:3], v[96:97]
	v_pk_fma_f32 v[78:79], v[78:79], v[0:1], v[94:95]
	s_nop 0
	v_cvt_pk_bf16_f32 v78, v78, v79
	v_cvt_pk_bf16_f32 v79, v76, v77
	global_store_dwordx2 v[88:89], v[78:79], off offset:512
	v_pk_mul_f32 v[76:77], v[82:83], v[48:49] op_sel_hi:[1,0]
	v_pk_mul_f32 v[78:79], v[80:81], v[48:49] op_sel_hi:[1,0]
	v_pk_fma_f32 v[76:77], v[76:77], v[0:1], v[94:95]
	v_pk_fma_f32 v[78:79], v[78:79], v[2:3], v[96:97]
	v_cvt_pk_bf16_f32 v76, v76, v77
	v_cvt_pk_bf16_f32 v77, v78, v79
	global_store_dwordx2 v[88:89], v[76:77], off offset:2560
	v_pk_mul_f32 v[76:77], v[86:87], v[54:55] op_sel_hi:[1,0]
	v_pk_mul_f32 v[78:79], v[84:85], v[54:55] op_sel_hi:[1,0]
	v_pk_fma_f32 v[76:77], v[76:77], v[0:1], v[94:95]
	v_pk_fma_f32 v[78:79], v[78:79], v[2:3], v[96:97]
	v_pk_fma_f32 v[2:3], v[2:3], v[72:73], v[96:97]
	v_pk_fma_f32 v[0:1], v[0:1], v[74:75], v[94:95]
	v_cvt_pk_bf16_f32 v76, v76, v77
	v_cvt_pk_bf16_f32 v77, v78, v79
	v_lshl_add_u64 v[78:79], v[22:23], 0, s[16:17]
	v_cvt_pk_bf16_f32 v0, v0, v1
	v_cvt_pk_bf16_f32 v1, v2, v3
	v_lshl_add_u64 v[2:3], v[22:23], 0, s[10:11]
	global_store_dwordx2 v[78:79], v[76:77], off
	global_store_dwordx2 v[2:3], v[0:1], off
	global_load_dwordx4 v[0:3], v[24:25], off
	s_nop 0
	global_load_dwordx4 v[72:75], v192, s[12:13]
	global_load_dwordx4 v[76:79], v192, s[0:1]
	s_waitcnt vmcnt(1)
	v_pk_add_f32 v[74:75], v[74:75], 1.0 op_sel_hi:[1,0]
	v_pk_add_f32 v[72:73], v[72:73], 1.0 op_sel_hi:[1,0]
	v_pk_mul_f32 v[2:3], v[2:3], v[74:75]
	v_pk_mul_f32 v[0:1], v[0:1], v[72:73]
	s_waitcnt vmcnt(0)
	v_pk_fma_f32 v[60:61], v[60:61], v[2:3], v[78:79]
	v_pk_fma_f32 v[66:67], v[66:67], v[0:1], v[76:77]
	v_pk_fma_f32 v[62:63], v[62:63], v[2:3], v[78:79]
	v_cvt_pk_bf16_f32 v66, v66, v67
	v_cvt_pk_bf16_f32 v67, v60, v61
	v_pk_mul_f32 v[60:61], v[68:69], v[48:49] op_sel_hi:[1,0]
	global_store_dwordx2 v[88:89], v[66:67], off offset:1024
	v_pk_fma_f32 v[60:61], v[60:61], v[0:1], v[76:77]
	s_nop 0
	v_cvt_pk_bf16_f32 v60, v60, v61
	v_cvt_pk_bf16_f32 v61, v62, v63
	global_store_dwordx2 v[88:89], v[60:61], off offset:3072
	v_pk_mul_f32 v[60:61], v[70:71], v[54:55] op_sel_hi:[1,0]
	v_pk_mul_f32 v[62:63], v[64:65], v[54:55] op_sel_hi:[1,0]
	v_pk_fma_f32 v[60:61], v[60:61], v[0:1], v[76:77]
	v_pk_fma_f32 v[62:63], v[62:63], v[2:3], v[78:79]
	v_pk_fma_f32 v[2:3], v[56:57], v[2:3], v[78:79]
	v_pk_fma_f32 v[0:1], v[58:59], v[0:1], v[76:77]
	v_cvt_pk_bf16_f32 v60, v60, v61
	v_cvt_pk_bf16_f32 v61, v62, v63
	v_lshl_add_u64 v[62:63], v[26:27], 0, s[16:17]
	v_cvt_pk_bf16_f32 v0, v0, v1
	v_cvt_pk_bf16_f32 v1, v2, v3
	v_lshl_add_u64 v[2:3], v[26:27], 0, s[10:11]
	global_store_dwordx2 v[62:63], v[60:61], off
	global_store_dwordx2 v[2:3], v[0:1], off
	global_load_dwordx4 v[0:3], v[28:29], off
	s_nop 0
	global_load_dwordx4 v[56:59], v193, s[12:13]
	global_load_dwordx4 v[60:63], v193, s[0:1]
	s_waitcnt vmcnt(1)
	v_pk_add_f32 v[58:59], v[58:59], 1.0 op_sel_hi:[1,0]
	v_pk_add_f32 v[56:57], v[56:57], 1.0 op_sel_hi:[1,0]
	v_pk_mul_f32 v[2:3], v[2:3], v[58:59]
	v_pk_mul_f32 v[0:1], v[0:1], v[56:57]
	s_waitcnt vmcnt(0)
	v_pk_fma_f32 v[32:33], v[32:33], v[2:3], v[62:63]
	v_pk_fma_f32 v[34:35], v[34:35], v[0:1], v[60:61]
	s_nop 0
	v_cvt_pk_bf16_f32 v34, v34, v35
	v_cvt_pk_bf16_f32 v35, v32, v33
	global_store_dwordx2 v[88:89], v[34:35], off offset:1536
	v_pk_mul_f32 v[32:33], v[38:39], v[48:49] op_sel_hi:[1,0]
	v_pk_mul_f32 v[34:35], v[36:37], v[48:49] op_sel_hi:[1,0]
	v_pk_fma_f32 v[32:33], v[32:33], v[0:1], v[60:61]
	v_pk_fma_f32 v[34:35], v[34:35], v[2:3], v[62:63]
	v_cvt_pk_bf16_f32 v32, v32, v33
	v_cvt_pk_bf16_f32 v33, v34, v35
	global_store_dwordx2 v[88:89], v[32:33], off offset:3584
	v_pk_mul_f32 v[32:33], v[42:43], v[54:55] op_sel_hi:[1,0]
	v_pk_mul_f32 v[34:35], v[40:41], v[54:55] op_sel_hi:[1,0]
	v_pk_fma_f32 v[32:33], v[32:33], v[0:1], v[60:61]
	v_pk_fma_f32 v[34:35], v[34:35], v[2:3], v[62:63]
	v_cvt_pk_bf16_f32 v32, v32, v33
	v_cvt_pk_bf16_f32 v33, v34, v35
	v_lshl_add_u64 v[34:35], v[30:31], 0, s[16:17]
	global_store_dwordx2 v[34:35], v[32:33], off
	v_pk_mul_f32 v[32:33], v[46:47], v[52:53] op_sel_hi:[1,0]
	v_pk_mul_f32 v[34:35], v[44:45], v[52:53] op_sel_hi:[1,0]
	v_pk_fma_f32 v[0:1], v[32:33], v[0:1], v[60:61]
	v_pk_fma_f32 v[2:3], v[34:35], v[2:3], v[62:63]
	v_cvt_pk_bf16_f32 v0, v0, v1
	v_cvt_pk_bf16_f32 v1, v2, v3
	v_lshl_add_u64 v[2:3], v[30:31], 0, s[10:11]
	global_store_dwordx2 v[2:3], v[0:1], off
	s_cbranch_scc1 .LBB0_912
